# P11 final rmsnorm loop rewritten by hand: hoisted gain vector, double-buffered rows, no per-chunk vmcnt(0)
# speedup vs baseline: 1.0004x; 1.0004x over previous
.LBB0_1211:
	s_cmp_lt_i32 s70, 12
	s_cselect_b64 s[0:1], -1, 0
	s_and_b64 s[0:1], s[0:1], s[2:3]
	s_cmpk_lt_i32 s34, 0x4000
	s_cselect_b64 s[2:3], -1, 0
	s_and_b64 s[0:1], s[0:1], s[2:3]
	s_andn2_b64 vcc, exec, s[0:1]
	s_cbranch_vccnz .LBB0_1214
	v_lshlrev_b32_e32 v0, 4, v146
	v_lshlrev_b32_e32 v1, 3, v146
	v_xor_b32_e32 v2, 1, v146
	v_xor_b32_e32 v3, 2, v146
	v_xor_b32_e32 v4, 4, v146
	v_xor_b32_e32 v5, 8, v146
	v_xor_b32_e32 v6, 16, v146
	v_xor_b32_e32 v7, 32, v146
	v_lshlrev_b32_e32 v2, 2, v2
	v_lshlrev_b32_e32 v3, 2, v3
	v_lshlrev_b32_e32 v4, 2, v4
	v_lshlrev_b32_e32 v5, 2, v5
	v_lshlrev_b32_e32 v6, 2, v6
	v_lshlrev_b32_e32 v7, 2, v7
	v_mov_b32_e32 v8, 0x358637bd
	v_mov_b32_e32 v9, 0x260
	s_mov_b32 s0, 0xf800000
	s_add_u32 s4, s26, 0x1000
	s_addc_u32 s5, s27, 0
	global_load_dwordx4 v[20:23], v0, s[4:5] offset:-4096
	global_load_dwordx4 v[24:27], v0, s[4:5] offset:-3072
	global_load_dwordx4 v[28:31], v0, s[4:5] offset:-2048
	global_load_dwordx4 v[32:35], v0, s[4:5] offset:-1024
	global_load_dwordx4 v[36:39], v0, s[4:5] offset:0
	global_load_dwordx4 v[40:43], v0, s[4:5] offset:1024
	global_load_dwordx4 v[44:47], v0, s[4:5] offset:2048
	global_load_dwordx4 v[48:51], v0, s[4:5] offset:3072
	s_lshl_b32 s6, s34, 13
	s_add_u32 s6, s6, 0x1000
	s_add_u32 s6, s28, s6
	s_addc_u32 s7, s29, 0
	s_mov_b64 s[8:9], s[6:7]
	global_load_dwordx4 v[52:55], v0, s[6:7] offset:-4096
	global_load_dwordx4 v[56:59], v0, s[6:7] offset:-3072
	global_load_dwordx4 v[60:63], v0, s[6:7] offset:-2048
	global_load_dwordx4 v[64:67], v0, s[6:7] offset:-1024
	global_load_dwordx4 v[68:71], v0, s[6:7] offset:0
	global_load_dwordx4 v[72:75], v0, s[6:7] offset:1024
	global_load_dwordx4 v[76:79], v0, s[6:7] offset:2048
	global_load_dwordx4 v[80:83], v0, s[6:7] offset:3072
	s_add_u32 s6, s6, 0x1000000
	s_addc_u32 s7, s7, 0
	global_load_dwordx4 v[84:87], v0, s[6:7] offset:-4096
	global_load_dwordx4 v[88:91], v0, s[6:7] offset:-3072
	global_load_dwordx4 v[92:95], v0, s[6:7] offset:-2048
	global_load_dwordx4 v[96:99], v0, s[6:7] offset:-1024
	global_load_dwordx4 v[100:103], v0, s[6:7] offset:0
	global_load_dwordx4 v[104:107], v0, s[6:7] offset:1024
	global_load_dwordx4 v[108:111], v0, s[6:7] offset:2048
	global_load_dwordx4 v[112:115], v0, s[6:7] offset:3072
	s_waitcnt vmcnt(8)
	v_mul_f32_e32 v10, v52, v52
	v_mul_f32_e32 v11, v53, v53
	v_mul_f32_e32 v12, v54, v54
	v_mul_f32_e32 v13, v55, v55
	v_fmac_f32_e32 v10, v56, v56
	v_fmac_f32_e32 v11, v57, v57
	v_fmac_f32_e32 v12, v58, v58
	v_fmac_f32_e32 v13, v59, v59
	v_fmac_f32_e32 v10, v60, v60
	v_fmac_f32_e32 v11, v61, v61
	v_fmac_f32_e32 v12, v62, v62
	v_fmac_f32_e32 v13, v63, v63
	v_fmac_f32_e32 v10, v64, v64
	v_fmac_f32_e32 v11, v65, v65
	v_fmac_f32_e32 v12, v66, v66
	v_fmac_f32_e32 v13, v67, v67
	v_fmac_f32_e32 v10, v68, v68
	v_fmac_f32_e32 v11, v69, v69
	v_fmac_f32_e32 v12, v70, v70
	v_fmac_f32_e32 v13, v71, v71
	v_fmac_f32_e32 v10, v72, v72
	v_fmac_f32_e32 v11, v73, v73
	v_fmac_f32_e32 v12, v74, v74
	v_fmac_f32_e32 v13, v75, v75
	v_fmac_f32_e32 v10, v76, v76
	v_fmac_f32_e32 v11, v77, v77
	v_fmac_f32_e32 v12, v78, v78
	v_fmac_f32_e32 v13, v79, v79
	v_fmac_f32_e32 v10, v80, v80
	v_fmac_f32_e32 v11, v81, v81
	v_fmac_f32_e32 v12, v82, v82
	v_fmac_f32_e32 v13, v83, v83
	v_add_f32_e32 v10, v10, v11
	v_add_f32_e32 v12, v12, v13
	v_add_f32_e32 v10, v10, v12
	ds_bpermute_b32 v11, v2, v10
	s_waitcnt lgkmcnt(0)
	v_add_f32_e32 v10, v10, v11
	ds_bpermute_b32 v11, v3, v10
	s_waitcnt lgkmcnt(0)
	v_add_f32_e32 v10, v10, v11
	ds_bpermute_b32 v11, v4, v10
	s_waitcnt lgkmcnt(0)
	v_add_f32_e32 v10, v10, v11
	ds_bpermute_b32 v11, v5, v10
	s_waitcnt lgkmcnt(0)
	v_add_f32_e32 v10, v10, v11
	ds_bpermute_b32 v11, v6, v10
	s_waitcnt lgkmcnt(0)
	v_add_f32_e32 v10, v10, v11
	ds_bpermute_b32 v11, v7, v10
	s_waitcnt lgkmcnt(0)
	v_add_f32_e32 v10, v10, v11
	v_fmamk_f32 v10, v10, 0x3a000000, v8
	v_mul_f32_e32 v11, 0x4f800000, v10
	v_cmp_gt_f32_e32 vcc, s0, v10
	s_nop 1
	v_cndmask_b32_e32 v10, v10, v11, vcc
	v_sqrt_f32_e32 v11, v10
	s_nop 0
	v_add_u32_e32 v12, -1, v11
	v_add_u32_e32 v13, 1, v11
	v_fma_f32 v14, -v12, v11, v10
	v_fma_f32 v15, -v13, v11, v10
	v_cmp_ge_f32_e64 s[2:3], 0, v14
	s_nop 1
	v_cndmask_b32_e64 v11, v11, v12, s[2:3]
	v_cmp_lt_f32_e64 s[2:3], 0, v15
	s_nop 1
	v_cndmask_b32_e64 v11, v11, v13, s[2:3]
	v_mul_f32_e32 v12, 0x37800000, v11
	v_cndmask_b32_e32 v11, v11, v12, vcc
	v_cmp_class_f32_e32 vcc, v10, v9
	s_nop 1
	v_cndmask_b32_e32 v10, v11, v10, vcc
	v_div_scale_f32 v11, s[2:3], v10, v10, 1.0
	v_rcp_f32_e32 v12, v11
	v_div_scale_f32 v13, vcc, 1.0, v10, 1.0
	v_fma_f32 v14, -v11, v12, 1.0
	v_fmac_f32_e32 v12, v14, v12
	v_mul_f32_e32 v14, v13, v12
	v_fma_f32 v15, -v11, v14, v13
	v_fmac_f32_e32 v14, v15, v12
	v_fma_f32 v11, -v11, v14, v13
	v_div_fmas_f32 v11, v11, v12, v14
	v_div_fixup_f32 v10, v11, v10, 1.0
	v_mov_b32_e32 v18, v10
	v_pk_mul_f32 v[52:53], v[52:53], v[18:19] op_sel_hi:[1,0]
	v_pk_mul_f32 v[54:55], v[54:55], v[18:19] op_sel_hi:[1,0]
	v_pk_mul_f32 v[56:57], v[56:57], v[18:19] op_sel_hi:[1,0]
	v_pk_mul_f32 v[58:59], v[58:59], v[18:19] op_sel_hi:[1,0]
	v_pk_mul_f32 v[60:61], v[60:61], v[18:19] op_sel_hi:[1,0]
	v_pk_mul_f32 v[62:63], v[62:63], v[18:19] op_sel_hi:[1,0]
	v_pk_mul_f32 v[64:65], v[64:65], v[18:19] op_sel_hi:[1,0]
	v_pk_mul_f32 v[66:67], v[66:67], v[18:19] op_sel_hi:[1,0]
	v_pk_mul_f32 v[68:69], v[68:69], v[18:19] op_sel_hi:[1,0]
	v_pk_mul_f32 v[70:71], v[70:71], v[18:19] op_sel_hi:[1,0]
	v_pk_mul_f32 v[72:73], v[72:73], v[18:19] op_sel_hi:[1,0]
	v_pk_mul_f32 v[74:75], v[74:75], v[18:19] op_sel_hi:[1,0]
	v_pk_mul_f32 v[76:77], v[76:77], v[18:19] op_sel_hi:[1,0]
	v_pk_mul_f32 v[78:79], v[78:79], v[18:19] op_sel_hi:[1,0]
	v_pk_mul_f32 v[80:81], v[80:81], v[18:19] op_sel_hi:[1,0]
	v_pk_mul_f32 v[82:83], v[82:83], v[18:19] op_sel_hi:[1,0]
	v_pk_mul_f32 v[52:53], v[20:21], v[52:53]
	v_pk_mul_f32 v[54:55], v[22:23], v[54:55]
	v_pk_mul_f32 v[56:57], v[24:25], v[56:57]
	v_pk_mul_f32 v[58:59], v[26:27], v[58:59]
	v_pk_mul_f32 v[60:61], v[28:29], v[60:61]
	v_pk_mul_f32 v[62:63], v[30:31], v[62:63]
	v_pk_mul_f32 v[64:65], v[32:33], v[64:65]
	v_pk_mul_f32 v[66:67], v[34:35], v[66:67]
	v_pk_mul_f32 v[68:69], v[36:37], v[68:69]
	v_pk_mul_f32 v[70:71], v[38:39], v[70:71]
	v_pk_mul_f32 v[72:73], v[40:41], v[72:73]
	v_pk_mul_f32 v[74:75], v[42:43], v[74:75]
	v_pk_mul_f32 v[76:77], v[44:45], v[76:77]
	v_pk_mul_f32 v[78:79], v[46:47], v[78:79]
	v_pk_mul_f32 v[80:81], v[48:49], v[80:81]
	v_pk_mul_f32 v[82:83], v[50:51], v[82:83]
	global_store_dwordx4 v0, v[52:55], s[8:9] offset:-4096
	global_store_dwordx4 v0, v[56:59], s[8:9] offset:-3072
	global_store_dwordx4 v0, v[60:63], s[8:9] offset:-2048
	global_store_dwordx4 v0, v[64:67], s[8:9] offset:-1024
	global_store_dwordx4 v0, v[68:71], s[8:9] offset:0
	global_store_dwordx4 v0, v[72:75], s[8:9] offset:1024
	global_store_dwordx4 v0, v[76:79], s[8:9] offset:2048
	global_store_dwordx4 v0, v[80:83], s[8:9] offset:3072
	s_add_u32 s8, s8, 0x1000000
	s_addc_u32 s9, s9, 0
	s_add_u32 s6, s6, 0x1000000
	s_addc_u32 s7, s7, 0
	global_load_dwordx4 v[52:55], v0, s[6:7] offset:-4096
	global_load_dwordx4 v[56:59], v0, s[6:7] offset:-3072
	global_load_dwordx4 v[60:63], v0, s[6:7] offset:-2048
	global_load_dwordx4 v[64:67], v0, s[6:7] offset:-1024
	global_load_dwordx4 v[68:71], v0, s[6:7] offset:0
	global_load_dwordx4 v[72:75], v0, s[6:7] offset:1024
	global_load_dwordx4 v[76:79], v0, s[6:7] offset:2048
	global_load_dwordx4 v[80:83], v0, s[6:7] offset:3072
	s_waitcnt vmcnt(16)
	v_mul_f32_e32 v10, v84, v84
	v_mul_f32_e32 v11, v85, v85
	v_mul_f32_e32 v12, v86, v86
	v_mul_f32_e32 v13, v87, v87
	v_fmac_f32_e32 v10, v88, v88
	v_fmac_f32_e32 v11, v89, v89
	v_fmac_f32_e32 v12, v90, v90
	v_fmac_f32_e32 v13, v91, v91
	v_fmac_f32_e32 v10, v92, v92
	v_fmac_f32_e32 v11, v93, v93
	v_fmac_f32_e32 v12, v94, v94
	v_fmac_f32_e32 v13, v95, v95
	v_fmac_f32_e32 v10, v96, v96
	v_fmac_f32_e32 v11, v97, v97
	v_fmac_f32_e32 v12, v98, v98
	v_fmac_f32_e32 v13, v99, v99
	v_fmac_f32_e32 v10, v100, v100
	v_fmac_f32_e32 v11, v101, v101
	v_fmac_f32_e32 v12, v102, v102
	v_fmac_f32_e32 v13, v103, v103
	v_fmac_f32_e32 v10, v104, v104
	v_fmac_f32_e32 v11, v105, v105
	v_fmac_f32_e32 v12, v106, v106
	v_fmac_f32_e32 v13, v107, v107
	v_fmac_f32_e32 v10, v108, v108
	v_fmac_f32_e32 v11, v109, v109
	v_fmac_f32_e32 v12, v110, v110
	v_fmac_f32_e32 v13, v111, v111
	v_fmac_f32_e32 v10, v112, v112
	v_fmac_f32_e32 v11, v113, v113
	v_fmac_f32_e32 v12, v114, v114
	v_fmac_f32_e32 v13, v115, v115
	v_add_f32_e32 v10, v10, v11
	v_add_f32_e32 v12, v12, v13
	v_add_f32_e32 v10, v10, v12
	ds_bpermute_b32 v11, v2, v10
	s_waitcnt lgkmcnt(0)
	v_add_f32_e32 v10, v10, v11
	ds_bpermute_b32 v11, v3, v10
	s_waitcnt lgkmcnt(0)
	v_add_f32_e32 v10, v10, v11
	ds_bpermute_b32 v11, v4, v10
	s_waitcnt lgkmcnt(0)
	v_add_f32_e32 v10, v10, v11
	ds_bpermute_b32 v11, v5, v10
	s_waitcnt lgkmcnt(0)
	v_add_f32_e32 v10, v10, v11
	ds_bpermute_b32 v11, v6, v10
	s_waitcnt lgkmcnt(0)
	v_add_f32_e32 v10, v10, v11
	ds_bpermute_b32 v11, v7, v10
	s_waitcnt lgkmcnt(0)
	v_add_f32_e32 v10, v10, v11
	v_fmamk_f32 v10, v10, 0x3a000000, v8
	v_mul_f32_e32 v11, 0x4f800000, v10
	v_cmp_gt_f32_e32 vcc, s0, v10
	s_nop 1
	v_cndmask_b32_e32 v10, v10, v11, vcc
	v_sqrt_f32_e32 v11, v10
	s_nop 0
	v_add_u32_e32 v12, -1, v11
	v_add_u32_e32 v13, 1, v11
	v_fma_f32 v14, -v12, v11, v10
	v_fma_f32 v15, -v13, v11, v10
	v_cmp_ge_f32_e64 s[2:3], 0, v14
	s_nop 1
	v_cndmask_b32_e64 v11, v11, v12, s[2:3]
	v_cmp_lt_f32_e64 s[2:3], 0, v15
	s_nop 1
	v_cndmask_b32_e64 v11, v11, v13, s[2:3]
	v_mul_f32_e32 v12, 0x37800000, v11
	v_cndmask_b32_e32 v11, v11, v12, vcc
	v_cmp_class_f32_e32 vcc, v10, v9
	s_nop 1
	v_cndmask_b32_e32 v10, v11, v10, vcc
	v_div_scale_f32 v11, s[2:3], v10, v10, 1.0
	v_rcp_f32_e32 v12, v11
	v_div_scale_f32 v13, vcc, 1.0, v10, 1.0
	v_fma_f32 v14, -v11, v12, 1.0
	v_fmac_f32_e32 v12, v14, v12
	v_mul_f32_e32 v14, v13, v12
	v_fma_f32 v15, -v11, v14, v13
	v_fmac_f32_e32 v14, v15, v12
	v_fma_f32 v11, -v11, v14, v13
	v_div_fmas_f32 v11, v11, v12, v14
	v_div_fixup_f32 v10, v11, v10, 1.0
	v_mov_b32_e32 v18, v10
	v_pk_mul_f32 v[84:85], v[84:85], v[18:19] op_sel_hi:[1,0]
	v_pk_mul_f32 v[86:87], v[86:87], v[18:19] op_sel_hi:[1,0]
	v_pk_mul_f32 v[88:89], v[88:89], v[18:19] op_sel_hi:[1,0]
	v_pk_mul_f32 v[90:91], v[90:91], v[18:19] op_sel_hi:[1,0]
	v_pk_mul_f32 v[92:93], v[92:93], v[18:19] op_sel_hi:[1,0]
	v_pk_mul_f32 v[94:95], v[94:95], v[18:19] op_sel_hi:[1,0]
	v_pk_mul_f32 v[96:97], v[96:97], v[18:19] op_sel_hi:[1,0]
	v_pk_mul_f32 v[98:99], v[98:99], v[18:19] op_sel_hi:[1,0]
	v_pk_mul_f32 v[100:101], v[100:101], v[18:19] op_sel_hi:[1,0]
	v_pk_mul_f32 v[102:103], v[102:103], v[18:19] op_sel_hi:[1,0]
	v_pk_mul_f32 v[104:105], v[104:105], v[18:19] op_sel_hi:[1,0]
	v_pk_mul_f32 v[106:107], v[106:107], v[18:19] op_sel_hi:[1,0]
	v_pk_mul_f32 v[108:109], v[108:109], v[18:19] op_sel_hi:[1,0]
	v_pk_mul_f32 v[110:111], v[110:111], v[18:19] op_sel_hi:[1,0]
	v_pk_mul_f32 v[112:113], v[112:113], v[18:19] op_sel_hi:[1,0]
	v_pk_mul_f32 v[114:115], v[114:115], v[18:19] op_sel_hi:[1,0]
	v_pk_mul_f32 v[84:85], v[20:21], v[84:85]
	v_pk_mul_f32 v[86:87], v[22:23], v[86:87]
	v_pk_mul_f32 v[88:89], v[24:25], v[88:89]
	v_pk_mul_f32 v[90:91], v[26:27], v[90:91]
	v_pk_mul_f32 v[92:93], v[28:29], v[92:93]
	v_pk_mul_f32 v[94:95], v[30:31], v[94:95]
	v_pk_mul_f32 v[96:97], v[32:33], v[96:97]
	v_pk_mul_f32 v[98:99], v[34:35], v[98:99]
	v_pk_mul_f32 v[100:101], v[36:37], v[100:101]
	v_pk_mul_f32 v[102:103], v[38:39], v[102:103]
	v_pk_mul_f32 v[104:105], v[40:41], v[104:105]
	v_pk_mul_f32 v[106:107], v[42:43], v[106:107]
	v_pk_mul_f32 v[108:109], v[44:45], v[108:109]
	v_pk_mul_f32 v[110:111], v[46:47], v[110:111]
	v_pk_mul_f32 v[112:113], v[48:49], v[112:113]
	v_pk_mul_f32 v[114:115], v[50:51], v[114:115]
	global_store_dwordx4 v0, v[84:87], s[8:9] offset:-4096
	global_store_dwordx4 v0, v[88:91], s[8:9] offset:-3072
	global_store_dwordx4 v0, v[92:95], s[8:9] offset:-2048
	global_store_dwordx4 v0, v[96:99], s[8:9] offset:-1024
	global_store_dwordx4 v0, v[100:103], s[8:9] offset:0
	global_store_dwordx4 v0, v[104:107], s[8:9] offset:1024
	global_store_dwordx4 v0, v[108:111], s[8:9] offset:2048
	global_store_dwordx4 v0, v[112:115], s[8:9] offset:3072
	s_add_u32 s8, s8, 0x1000000
	s_addc_u32 s9, s9, 0
	s_add_u32 s6, s6, 0x1000000
	s_addc_u32 s7, s7, 0
	global_load_dwordx4 v[84:87], v0, s[6:7] offset:-4096
	global_load_dwordx4 v[88:91], v0, s[6:7] offset:-3072
	global_load_dwordx4 v[92:95], v0, s[6:7] offset:-2048
	global_load_dwordx4 v[96:99], v0, s[6:7] offset:-1024
	global_load_dwordx4 v[100:103], v0, s[6:7] offset:0
	global_load_dwordx4 v[104:107], v0, s[6:7] offset:1024
	global_load_dwordx4 v[108:111], v0, s[6:7] offset:2048
	global_load_dwordx4 v[112:115], v0, s[6:7] offset:3072
	s_waitcnt vmcnt(16)
	v_mul_f32_e32 v10, v52, v52
	v_mul_f32_e32 v11, v53, v53
	v_mul_f32_e32 v12, v54, v54
	v_mul_f32_e32 v13, v55, v55
	v_fmac_f32_e32 v10, v56, v56
	v_fmac_f32_e32 v11, v57, v57
	v_fmac_f32_e32 v12, v58, v58
	v_fmac_f32_e32 v13, v59, v59
	v_fmac_f32_e32 v10, v60, v60
	v_fmac_f32_e32 v11, v61, v61
	v_fmac_f32_e32 v12, v62, v62
	v_fmac_f32_e32 v13, v63, v63
	v_fmac_f32_e32 v10, v64, v64
	v_fmac_f32_e32 v11, v65, v65
	v_fmac_f32_e32 v12, v66, v66
	v_fmac_f32_e32 v13, v67, v67
	v_fmac_f32_e32 v10, v68, v68
	v_fmac_f32_e32 v11, v69, v69
	v_fmac_f32_e32 v12, v70, v70
	v_fmac_f32_e32 v13, v71, v71
	v_fmac_f32_e32 v10, v72, v72
	v_fmac_f32_e32 v11, v73, v73
	v_fmac_f32_e32 v12, v74, v74
	v_fmac_f32_e32 v13, v75, v75
	v_fmac_f32_e32 v10, v76, v76
	v_fmac_f32_e32 v11, v77, v77
	v_fmac_f32_e32 v12, v78, v78
	v_fmac_f32_e32 v13, v79, v79
	v_fmac_f32_e32 v10, v80, v80
	v_fmac_f32_e32 v11, v81, v81
	v_fmac_f32_e32 v12, v82, v82
	v_fmac_f32_e32 v13, v83, v83
	v_add_f32_e32 v10, v10, v11
	v_add_f32_e32 v12, v12, v13
	v_add_f32_e32 v10, v10, v12
	ds_bpermute_b32 v11, v2, v10
	s_waitcnt lgkmcnt(0)
	v_add_f32_e32 v10, v10, v11
	ds_bpermute_b32 v11, v3, v10
	s_waitcnt lgkmcnt(0)
	v_add_f32_e32 v10, v10, v11
	ds_bpermute_b32 v11, v4, v10
	s_waitcnt lgkmcnt(0)
	v_add_f32_e32 v10, v10, v11
	ds_bpermute_b32 v11, v5, v10
	s_waitcnt lgkmcnt(0)
	v_add_f32_e32 v10, v10, v11
	ds_bpermute_b32 v11, v6, v10
	s_waitcnt lgkmcnt(0)
	v_add_f32_e32 v10, v10, v11
	ds_bpermute_b32 v11, v7, v10
	s_waitcnt lgkmcnt(0)
	v_add_f32_e32 v10, v10, v11
	v_fmamk_f32 v10, v10, 0x3a000000, v8
	v_mul_f32_e32 v11, 0x4f800000, v10
	v_cmp_gt_f32_e32 vcc, s0, v10
	s_nop 1
	v_cndmask_b32_e32 v10, v10, v11, vcc
	v_sqrt_f32_e32 v11, v10
	s_nop 0
	v_add_u32_e32 v12, -1, v11
	v_add_u32_e32 v13, 1, v11
	v_fma_f32 v14, -v12, v11, v10
	v_fma_f32 v15, -v13, v11, v10
	v_cmp_ge_f32_e64 s[2:3], 0, v14
	s_nop 1
	v_cndmask_b32_e64 v11, v11, v12, s[2:3]
	v_cmp_lt_f32_e64 s[2:3], 0, v15
	s_nop 1
	v_cndmask_b32_e64 v11, v11, v13, s[2:3]
	v_mul_f32_e32 v12, 0x37800000, v11
	v_cndmask_b32_e32 v11, v11, v12, vcc
	v_cmp_class_f32_e32 vcc, v10, v9
	s_nop 1
	v_cndmask_b32_e32 v10, v11, v10, vcc
	v_div_scale_f32 v11, s[2:3], v10, v10, 1.0
	v_rcp_f32_e32 v12, v11
	v_div_scale_f32 v13, vcc, 1.0, v10, 1.0
	v_fma_f32 v14, -v11, v12, 1.0
	v_fmac_f32_e32 v12, v14, v12
	v_mul_f32_e32 v14, v13, v12
	v_fma_f32 v15, -v11, v14, v13
	v_fmac_f32_e32 v14, v15, v12
	v_fma_f32 v11, -v11, v14, v13
	v_div_fmas_f32 v11, v11, v12, v14
	v_div_fixup_f32 v10, v11, v10, 1.0
	v_mov_b32_e32 v18, v10
	v_pk_mul_f32 v[52:53], v[52:53], v[18:19] op_sel_hi:[1,0]
	v_pk_mul_f32 v[54:55], v[54:55], v[18:19] op_sel_hi:[1,0]
	v_pk_mul_f32 v[56:57], v[56:57], v[18:19] op_sel_hi:[1,0]
	v_pk_mul_f32 v[58:59], v[58:59], v[18:19] op_sel_hi:[1,0]
	v_pk_mul_f32 v[60:61], v[60:61], v[18:19] op_sel_hi:[1,0]
	v_pk_mul_f32 v[62:63], v[62:63], v[18:19] op_sel_hi:[1,0]
	v_pk_mul_f32 v[64:65], v[64:65], v[18:19] op_sel_hi:[1,0]
	v_pk_mul_f32 v[66:67], v[66:67], v[18:19] op_sel_hi:[1,0]
	v_pk_mul_f32 v[68:69], v[68:69], v[18:19] op_sel_hi:[1,0]
	v_pk_mul_f32 v[70:71], v[70:71], v[18:19] op_sel_hi:[1,0]
	v_pk_mul_f32 v[72:73], v[72:73], v[18:19] op_sel_hi:[1,0]
	v_pk_mul_f32 v[74:75], v[74:75], v[18:19] op_sel_hi:[1,0]
	v_pk_mul_f32 v[76:77], v[76:77], v[18:19] op_sel_hi:[1,0]
	v_pk_mul_f32 v[78:79], v[78:79], v[18:19] op_sel_hi:[1,0]
	v_pk_mul_f32 v[80:81], v[80:81], v[18:19] op_sel_hi:[1,0]
	v_pk_mul_f32 v[82:83], v[82:83], v[18:19] op_sel_hi:[1,0]
	v_pk_mul_f32 v[52:53], v[20:21], v[52:53]
	v_pk_mul_f32 v[54:55], v[22:23], v[54:55]
	v_pk_mul_f32 v[56:57], v[24:25], v[56:57]
	v_pk_mul_f32 v[58:59], v[26:27], v[58:59]
	v_pk_mul_f32 v[60:61], v[28:29], v[60:61]
	v_pk_mul_f32 v[62:63], v[30:31], v[62:63]
	v_pk_mul_f32 v[64:65], v[32:33], v[64:65]
	v_pk_mul_f32 v[66:67], v[34:35], v[66:67]
	v_pk_mul_f32 v[68:69], v[36:37], v[68:69]
	v_pk_mul_f32 v[70:71], v[38:39], v[70:71]
	v_pk_mul_f32 v[72:73], v[40:41], v[72:73]
	v_pk_mul_f32 v[74:75], v[42:43], v[74:75]
	v_pk_mul_f32 v[76:77], v[44:45], v[76:77]
	v_pk_mul_f32 v[78:79], v[46:47], v[78:79]
	v_pk_mul_f32 v[80:81], v[48:49], v[80:81]
	v_pk_mul_f32 v[82:83], v[50:51], v[82:83]
	global_store_dwordx4 v0, v[52:55], s[8:9] offset:-4096
	global_store_dwordx4 v0, v[56:59], s[8:9] offset:-3072
	global_store_dwordx4 v0, v[60:63], s[8:9] offset:-2048
	global_store_dwordx4 v0, v[64:67], s[8:9] offset:-1024
	global_store_dwordx4 v0, v[68:71], s[8:9] offset:0
	global_store_dwordx4 v0, v[72:75], s[8:9] offset:1024
	global_store_dwordx4 v0, v[76:79], s[8:9] offset:2048
	global_store_dwordx4 v0, v[80:83], s[8:9] offset:3072
	s_add_u32 s8, s8, 0x1000000
	s_addc_u32 s9, s9, 0
	s_add_u32 s6, s6, 0x1000000
	s_addc_u32 s7, s7, 0
	global_load_dwordx4 v[52:55], v0, s[6:7] offset:-4096
	global_load_dwordx4 v[56:59], v0, s[6:7] offset:-3072
	global_load_dwordx4 v[60:63], v0, s[6:7] offset:-2048
	global_load_dwordx4 v[64:67], v0, s[6:7] offset:-1024
	global_load_dwordx4 v[68:71], v0, s[6:7] offset:0
	global_load_dwordx4 v[72:75], v0, s[6:7] offset:1024
	global_load_dwordx4 v[76:79], v0, s[6:7] offset:2048
	global_load_dwordx4 v[80:83], v0, s[6:7] offset:3072
	s_waitcnt vmcnt(16)
	v_mul_f32_e32 v10, v84, v84
	v_mul_f32_e32 v11, v85, v85
	v_mul_f32_e32 v12, v86, v86
	v_mul_f32_e32 v13, v87, v87
	v_fmac_f32_e32 v10, v88, v88
	v_fmac_f32_e32 v11, v89, v89
	v_fmac_f32_e32 v12, v90, v90
	v_fmac_f32_e32 v13, v91, v91
	v_fmac_f32_e32 v10, v92, v92
	v_fmac_f32_e32 v11, v93, v93
	v_fmac_f32_e32 v12, v94, v94
	v_fmac_f32_e32 v13, v95, v95
	v_fmac_f32_e32 v10, v96, v96
	v_fmac_f32_e32 v11, v97, v97
	v_fmac_f32_e32 v12, v98, v98
	v_fmac_f32_e32 v13, v99, v99
	v_fmac_f32_e32 v10, v100, v100
	v_fmac_f32_e32 v11, v101, v101
	v_fmac_f32_e32 v12, v102, v102
	v_fmac_f32_e32 v13, v103, v103
	v_fmac_f32_e32 v10, v104, v104
	v_fmac_f32_e32 v11, v105, v105
	v_fmac_f32_e32 v12, v106, v106
	v_fmac_f32_e32 v13, v107, v107
	v_fmac_f32_e32 v10, v108, v108
	v_fmac_f32_e32 v11, v109, v109
	v_fmac_f32_e32 v12, v110, v110
	v_fmac_f32_e32 v13, v111, v111
	v_fmac_f32_e32 v10, v112, v112
	v_fmac_f32_e32 v11, v113, v113
	v_fmac_f32_e32 v12, v114, v114
	v_fmac_f32_e32 v13, v115, v115
	v_add_f32_e32 v10, v10, v11
	v_add_f32_e32 v12, v12, v13
	v_add_f32_e32 v10, v10, v12
	ds_bpermute_b32 v11, v2, v10
	s_waitcnt lgkmcnt(0)
	v_add_f32_e32 v10, v10, v11
	ds_bpermute_b32 v11, v3, v10
	s_waitcnt lgkmcnt(0)
	v_add_f32_e32 v10, v10, v11
	ds_bpermute_b32 v11, v4, v10
	s_waitcnt lgkmcnt(0)
	v_add_f32_e32 v10, v10, v11
	ds_bpermute_b32 v11, v5, v10
	s_waitcnt lgkmcnt(0)
	v_add_f32_e32 v10, v10, v11
	ds_bpermute_b32 v11, v6, v10
	s_waitcnt lgkmcnt(0)
	v_add_f32_e32 v10, v10, v11
	ds_bpermute_b32 v11, v7, v10
	s_waitcnt lgkmcnt(0)
	v_add_f32_e32 v10, v10, v11
	v_fmamk_f32 v10, v10, 0x3a000000, v8
	v_mul_f32_e32 v11, 0x4f800000, v10
	v_cmp_gt_f32_e32 vcc, s0, v10
	s_nop 1
	v_cndmask_b32_e32 v10, v10, v11, vcc
	v_sqrt_f32_e32 v11, v10
	s_nop 0
	v_add_u32_e32 v12, -1, v11
	v_add_u32_e32 v13, 1, v11
	v_fma_f32 v14, -v12, v11, v10
	v_fma_f32 v15, -v13, v11, v10
	v_cmp_ge_f32_e64 s[2:3], 0, v14
	s_nop 1
	v_cndmask_b32_e64 v11, v11, v12, s[2:3]
	v_cmp_lt_f32_e64 s[2:3], 0, v15
	s_nop 1
	v_cndmask_b32_e64 v11, v11, v13, s[2:3]
	v_mul_f32_e32 v12, 0x37800000, v11
	v_cndmask_b32_e32 v11, v11, v12, vcc
	v_cmp_class_f32_e32 vcc, v10, v9
	s_nop 1
	v_cndmask_b32_e32 v10, v11, v10, vcc
	v_div_scale_f32 v11, s[2:3], v10, v10, 1.0
	v_rcp_f32_e32 v12, v11
	v_div_scale_f32 v13, vcc, 1.0, v10, 1.0
	v_fma_f32 v14, -v11, v12, 1.0
	v_fmac_f32_e32 v12, v14, v12
	v_mul_f32_e32 v14, v13, v12
	v_fma_f32 v15, -v11, v14, v13
	v_fmac_f32_e32 v14, v15, v12
	v_fma_f32 v11, -v11, v14, v13
	v_div_fmas_f32 v11, v11, v12, v14
	v_div_fixup_f32 v10, v11, v10, 1.0
	v_mov_b32_e32 v18, v10
	v_pk_mul_f32 v[84:85], v[84:85], v[18:19] op_sel_hi:[1,0]
	v_pk_mul_f32 v[86:87], v[86:87], v[18:19] op_sel_hi:[1,0]
	v_pk_mul_f32 v[88:89], v[88:89], v[18:19] op_sel_hi:[1,0]
	v_pk_mul_f32 v[90:91], v[90:91], v[18:19] op_sel_hi:[1,0]
	v_pk_mul_f32 v[92:93], v[92:93], v[18:19] op_sel_hi:[1,0]
	v_pk_mul_f32 v[94:95], v[94:95], v[18:19] op_sel_hi:[1,0]
	v_pk_mul_f32 v[96:97], v[96:97], v[18:19] op_sel_hi:[1,0]
	v_pk_mul_f32 v[98:99], v[98:99], v[18:19] op_sel_hi:[1,0]
	v_pk_mul_f32 v[100:101], v[100:101], v[18:19] op_sel_hi:[1,0]
	v_pk_mul_f32 v[102:103], v[102:103], v[18:19] op_sel_hi:[1,0]
	v_pk_mul_f32 v[104:105], v[104:105], v[18:19] op_sel_hi:[1,0]
	v_pk_mul_f32 v[106:107], v[106:107], v[18:19] op_sel_hi:[1,0]
	v_pk_mul_f32 v[108:109], v[108:109], v[18:19] op_sel_hi:[1,0]
	v_pk_mul_f32 v[110:111], v[110:111], v[18:19] op_sel_hi:[1,0]
	v_pk_mul_f32 v[112:113], v[112:113], v[18:19] op_sel_hi:[1,0]
	v_pk_mul_f32 v[114:115], v[114:115], v[18:19] op_sel_hi:[1,0]
	v_pk_mul_f32 v[84:85], v[20:21], v[84:85]
	v_pk_mul_f32 v[86:87], v[22:23], v[86:87]
	v_pk_mul_f32 v[88:89], v[24:25], v[88:89]
	v_pk_mul_f32 v[90:91], v[26:27], v[90:91]
	v_pk_mul_f32 v[92:93], v[28:29], v[92:93]
	v_pk_mul_f32 v[94:95], v[30:31], v[94:95]
	v_pk_mul_f32 v[96:97], v[32:33], v[96:97]
	v_pk_mul_f32 v[98:99], v[34:35], v[98:99]
	v_pk_mul_f32 v[100:101], v[36:37], v[100:101]
	v_pk_mul_f32 v[102:103], v[38:39], v[102:103]
	v_pk_mul_f32 v[104:105], v[40:41], v[104:105]
	v_pk_mul_f32 v[106:107], v[42:43], v[106:107]
	v_pk_mul_f32 v[108:109], v[44:45], v[108:109]
	v_pk_mul_f32 v[110:111], v[46:47], v[110:111]
	v_pk_mul_f32 v[112:113], v[48:49], v[112:113]
	v_pk_mul_f32 v[114:115], v[50:51], v[114:115]
	global_store_dwordx4 v0, v[84:87], s[8:9] offset:-4096
	global_store_dwordx4 v0, v[88:91], s[8:9] offset:-3072
	global_store_dwordx4 v0, v[92:95], s[8:9] offset:-2048
	global_store_dwordx4 v0, v[96:99], s[8:9] offset:-1024
	global_store_dwordx4 v0, v[100:103], s[8:9] offset:0
	global_store_dwordx4 v0, v[104:107], s[8:9] offset:1024
	global_store_dwordx4 v0, v[108:111], s[8:9] offset:2048
	global_store_dwordx4 v0, v[112:115], s[8:9] offset:3072
	s_add_u32 s8, s8, 0x1000000
	s_addc_u32 s9, s9, 0
	s_add_u32 s6, s6, 0x1000000
	s_addc_u32 s7, s7, 0
	global_load_dwordx4 v[84:87], v0, s[6:7] offset:-4096
	global_load_dwordx4 v[88:91], v0, s[6:7] offset:-3072
	global_load_dwordx4 v[92:95], v0, s[6:7] offset:-2048
	global_load_dwordx4 v[96:99], v0, s[6:7] offset:-1024
	global_load_dwordx4 v[100:103], v0, s[6:7] offset:0
	global_load_dwordx4 v[104:107], v0, s[6:7] offset:1024
	global_load_dwordx4 v[108:111], v0, s[6:7] offset:2048
	global_load_dwordx4 v[112:115], v0, s[6:7] offset:3072
	s_waitcnt vmcnt(16)
	v_mul_f32_e32 v10, v52, v52
	v_mul_f32_e32 v11, v53, v53
	v_mul_f32_e32 v12, v54, v54
	v_mul_f32_e32 v13, v55, v55
	v_fmac_f32_e32 v10, v56, v56
	v_fmac_f32_e32 v11, v57, v57
	v_fmac_f32_e32 v12, v58, v58
	v_fmac_f32_e32 v13, v59, v59
	v_fmac_f32_e32 v10, v60, v60
	v_fmac_f32_e32 v11, v61, v61
	v_fmac_f32_e32 v12, v62, v62
	v_fmac_f32_e32 v13, v63, v63
	v_fmac_f32_e32 v10, v64, v64
	v_fmac_f32_e32 v11, v65, v65
	v_fmac_f32_e32 v12, v66, v66
	v_fmac_f32_e32 v13, v67, v67
	v_fmac_f32_e32 v10, v68, v68
	v_fmac_f32_e32 v11, v69, v69
	v_fmac_f32_e32 v12, v70, v70
	v_fmac_f32_e32 v13, v71, v71
	v_fmac_f32_e32 v10, v72, v72
	v_fmac_f32_e32 v11, v73, v73
	v_fmac_f32_e32 v12, v74, v74
	v_fmac_f32_e32 v13, v75, v75
	v_fmac_f32_e32 v10, v76, v76
	v_fmac_f32_e32 v11, v77, v77
	v_fmac_f32_e32 v12, v78, v78
	v_fmac_f32_e32 v13, v79, v79
	v_fmac_f32_e32 v10, v80, v80
	v_fmac_f32_e32 v11, v81, v81
	v_fmac_f32_e32 v12, v82, v82
	v_fmac_f32_e32 v13, v83, v83
	v_add_f32_e32 v10, v10, v11
	v_add_f32_e32 v12, v12, v13
	v_add_f32_e32 v10, v10, v12
	ds_bpermute_b32 v11, v2, v10
	s_waitcnt lgkmcnt(0)
	v_add_f32_e32 v10, v10, v11
	ds_bpermute_b32 v11, v3, v10
	s_waitcnt lgkmcnt(0)
	v_add_f32_e32 v10, v10, v11
	ds_bpermute_b32 v11, v4, v10
	s_waitcnt lgkmcnt(0)
	v_add_f32_e32 v10, v10, v11
	ds_bpermute_b32 v11, v5, v10
	s_waitcnt lgkmcnt(0)
	v_add_f32_e32 v10, v10, v11
	ds_bpermute_b32 v11, v6, v10
	s_waitcnt lgkmcnt(0)
	v_add_f32_e32 v10, v10, v11
	ds_bpermute_b32 v11, v7, v10
	s_waitcnt lgkmcnt(0)
	v_add_f32_e32 v10, v10, v11
	v_fmamk_f32 v10, v10, 0x3a000000, v8
	v_mul_f32_e32 v11, 0x4f800000, v10
	v_cmp_gt_f32_e32 vcc, s0, v10
	s_nop 1
	v_cndmask_b32_e32 v10, v10, v11, vcc
	v_sqrt_f32_e32 v11, v10
	s_nop 0
	v_add_u32_e32 v12, -1, v11
	v_add_u32_e32 v13, 1, v11
	v_fma_f32 v14, -v12, v11, v10
	v_fma_f32 v15, -v13, v11, v10
	v_cmp_ge_f32_e64 s[2:3], 0, v14
	s_nop 1
	v_cndmask_b32_e64 v11, v11, v12, s[2:3]
	v_cmp_lt_f32_e64 s[2:3], 0, v15
	s_nop 1
	v_cndmask_b32_e64 v11, v11, v13, s[2:3]
	v_mul_f32_e32 v12, 0x37800000, v11
	v_cndmask_b32_e32 v11, v11, v12, vcc
	v_cmp_class_f32_e32 vcc, v10, v9
	s_nop 1
	v_cndmask_b32_e32 v10, v11, v10, vcc
	v_div_scale_f32 v11, s[2:3], v10, v10, 1.0
	v_rcp_f32_e32 v12, v11
	v_div_scale_f32 v13, vcc, 1.0, v10, 1.0
	v_fma_f32 v14, -v11, v12, 1.0
	v_fmac_f32_e32 v12, v14, v12
	v_mul_f32_e32 v14, v13, v12
	v_fma_f32 v15, -v11, v14, v13
	v_fmac_f32_e32 v14, v15, v12
	v_fma_f32 v11, -v11, v14, v13
	v_div_fmas_f32 v11, v11, v12, v14
	v_div_fixup_f32 v10, v11, v10, 1.0
	v_mov_b32_e32 v18, v10
	v_pk_mul_f32 v[52:53], v[52:53], v[18:19] op_sel_hi:[1,0]
	v_pk_mul_f32 v[54:55], v[54:55], v[18:19] op_sel_hi:[1,0]
	v_pk_mul_f32 v[56:57], v[56:57], v[18:19] op_sel_hi:[1,0]
	v_pk_mul_f32 v[58:59], v[58:59], v[18:19] op_sel_hi:[1,0]
	v_pk_mul_f32 v[60:61], v[60:61], v[18:19] op_sel_hi:[1,0]
	v_pk_mul_f32 v[62:63], v[62:63], v[18:19] op_sel_hi:[1,0]
	v_pk_mul_f32 v[64:65], v[64:65], v[18:19] op_sel_hi:[1,0]
	v_pk_mul_f32 v[66:67], v[66:67], v[18:19] op_sel_hi:[1,0]
	v_pk_mul_f32 v[68:69], v[68:69], v[18:19] op_sel_hi:[1,0]
	v_pk_mul_f32 v[70:71], v[70:71], v[18:19] op_sel_hi:[1,0]
	v_pk_mul_f32 v[72:73], v[72:73], v[18:19] op_sel_hi:[1,0]
	v_pk_mul_f32 v[74:75], v[74:75], v[18:19] op_sel_hi:[1,0]
	v_pk_mul_f32 v[76:77], v[76:77], v[18:19] op_sel_hi:[1,0]
	v_pk_mul_f32 v[78:79], v[78:79], v[18:19] op_sel_hi:[1,0]
	v_pk_mul_f32 v[80:81], v[80:81], v[18:19] op_sel_hi:[1,0]
	v_pk_mul_f32 v[82:83], v[82:83], v[18:19] op_sel_hi:[1,0]
	v_pk_mul_f32 v[52:53], v[20:21], v[52:53]
	v_pk_mul_f32 v[54:55], v[22:23], v[54:55]
	v_pk_mul_f32 v[56:57], v[24:25], v[56:57]
	v_pk_mul_f32 v[58:59], v[26:27], v[58:59]
	v_pk_mul_f32 v[60:61], v[28:29], v[60:61]
	v_pk_mul_f32 v[62:63], v[30:31], v[62:63]
	v_pk_mul_f32 v[64:65], v[32:33], v[64:65]
	v_pk_mul_f32 v[66:67], v[34:35], v[66:67]
	v_pk_mul_f32 v[68:69], v[36:37], v[68:69]
	v_pk_mul_f32 v[70:71], v[38:39], v[70:71]
	v_pk_mul_f32 v[72:73], v[40:41], v[72:73]
	v_pk_mul_f32 v[74:75], v[42:43], v[74:75]
	v_pk_mul_f32 v[76:77], v[44:45], v[76:77]
	v_pk_mul_f32 v[78:79], v[46:47], v[78:79]
	v_pk_mul_f32 v[80:81], v[48:49], v[80:81]
	v_pk_mul_f32 v[82:83], v[50:51], v[82:83]
	global_store_dwordx4 v0, v[52:55], s[8:9] offset:-4096
	global_store_dwordx4 v0, v[56:59], s[8:9] offset:-3072
	global_store_dwordx4 v0, v[60:63], s[8:9] offset:-2048
	global_store_dwordx4 v0, v[64:67], s[8:9] offset:-1024
	global_store_dwordx4 v0, v[68:71], s[8:9] offset:0
	global_store_dwordx4 v0, v[72:75], s[8:9] offset:1024
	global_store_dwordx4 v0, v[76:79], s[8:9] offset:2048
	global_store_dwordx4 v0, v[80:83], s[8:9] offset:3072
	s_add_u32 s8, s8, 0x1000000
	s_addc_u32 s9, s9, 0
	s_add_u32 s6, s6, 0x1000000
	s_addc_u32 s7, s7, 0
	global_load_dwordx4 v[52:55], v0, s[6:7] offset:-4096
	global_load_dwordx4 v[56:59], v0, s[6:7] offset:-3072
	global_load_dwordx4 v[60:63], v0, s[6:7] offset:-2048
	global_load_dwordx4 v[64:67], v0, s[6:7] offset:-1024
	global_load_dwordx4 v[68:71], v0, s[6:7] offset:0
	global_load_dwordx4 v[72:75], v0, s[6:7] offset:1024
	global_load_dwordx4 v[76:79], v0, s[6:7] offset:2048
	global_load_dwordx4 v[80:83], v0, s[6:7] offset:3072
	s_waitcnt vmcnt(16)
	v_mul_f32_e32 v10, v84, v84
	v_mul_f32_e32 v11, v85, v85
	v_mul_f32_e32 v12, v86, v86
	v_mul_f32_e32 v13, v87, v87
	v_fmac_f32_e32 v10, v88, v88
	v_fmac_f32_e32 v11, v89, v89
	v_fmac_f32_e32 v12, v90, v90
	v_fmac_f32_e32 v13, v91, v91
	v_fmac_f32_e32 v10, v92, v92
	v_fmac_f32_e32 v11, v93, v93
	v_fmac_f32_e32 v12, v94, v94
	v_fmac_f32_e32 v13, v95, v95
	v_fmac_f32_e32 v10, v96, v96
	v_fmac_f32_e32 v11, v97, v97
	v_fmac_f32_e32 v12, v98, v98
	v_fmac_f32_e32 v13, v99, v99
	v_fmac_f32_e32 v10, v100, v100
	v_fmac_f32_e32 v11, v101, v101
	v_fmac_f32_e32 v12, v102, v102
	v_fmac_f32_e32 v13, v103, v103
	v_fmac_f32_e32 v10, v104, v104
	v_fmac_f32_e32 v11, v105, v105
	v_fmac_f32_e32 v12, v106, v106
	v_fmac_f32_e32 v13, v107, v107
	v_fmac_f32_e32 v10, v108, v108
	v_fmac_f32_e32 v11, v109, v109
	v_fmac_f32_e32 v12, v110, v110
	v_fmac_f32_e32 v13, v111, v111
	v_fmac_f32_e32 v10, v112, v112
	v_fmac_f32_e32 v11, v113, v113
	v_fmac_f32_e32 v12, v114, v114
	v_fmac_f32_e32 v13, v115, v115
	v_add_f32_e32 v10, v10, v11
	v_add_f32_e32 v12, v12, v13
	v_add_f32_e32 v10, v10, v12
	ds_bpermute_b32 v11, v2, v10
	s_waitcnt lgkmcnt(0)
	v_add_f32_e32 v10, v10, v11
	ds_bpermute_b32 v11, v3, v10
	s_waitcnt lgkmcnt(0)
	v_add_f32_e32 v10, v10, v11
	ds_bpermute_b32 v11, v4, v10
	s_waitcnt lgkmcnt(0)
	v_add_f32_e32 v10, v10, v11
	ds_bpermute_b32 v11, v5, v10
	s_waitcnt lgkmcnt(0)
	v_add_f32_e32 v10, v10, v11
	ds_bpermute_b32 v11, v6, v10
	s_waitcnt lgkmcnt(0)
	v_add_f32_e32 v10, v10, v11
	ds_bpermute_b32 v11, v7, v10
	s_waitcnt lgkmcnt(0)
	v_add_f32_e32 v10, v10, v11
	v_fmamk_f32 v10, v10, 0x3a000000, v8
	v_mul_f32_e32 v11, 0x4f800000, v10
	v_cmp_gt_f32_e32 vcc, s0, v10
	s_nop 1
	v_cndmask_b32_e32 v10, v10, v11, vcc
	v_sqrt_f32_e32 v11, v10
	s_nop 0
	v_add_u32_e32 v12, -1, v11
	v_add_u32_e32 v13, 1, v11
	v_fma_f32 v14, -v12, v11, v10
	v_fma_f32 v15, -v13, v11, v10
	v_cmp_ge_f32_e64 s[2:3], 0, v14
	s_nop 1
	v_cndmask_b32_e64 v11, v11, v12, s[2:3]
	v_cmp_lt_f32_e64 s[2:3], 0, v15
	s_nop 1
	v_cndmask_b32_e64 v11, v11, v13, s[2:3]
	v_mul_f32_e32 v12, 0x37800000, v11
	v_cndmask_b32_e32 v11, v11, v12, vcc
	v_cmp_class_f32_e32 vcc, v10, v9
	s_nop 1
	v_cndmask_b32_e32 v10, v11, v10, vcc
	v_div_scale_f32 v11, s[2:3], v10, v10, 1.0
	v_rcp_f32_e32 v12, v11
	v_div_scale_f32 v13, vcc, 1.0, v10, 1.0
	v_fma_f32 v14, -v11, v12, 1.0
	v_fmac_f32_e32 v12, v14, v12
	v_mul_f32_e32 v14, v13, v12
	v_fma_f32 v15, -v11, v14, v13
	v_fmac_f32_e32 v14, v15, v12
	v_fma_f32 v11, -v11, v14, v13
	v_div_fmas_f32 v11, v11, v12, v14
	v_div_fixup_f32 v10, v11, v10, 1.0
	v_mov_b32_e32 v18, v10
	v_pk_mul_f32 v[84:85], v[84:85], v[18:19] op_sel_hi:[1,0]
	v_pk_mul_f32 v[86:87], v[86:87], v[18:19] op_sel_hi:[1,0]
	v_pk_mul_f32 v[88:89], v[88:89], v[18:19] op_sel_hi:[1,0]
	v_pk_mul_f32 v[90:91], v[90:91], v[18:19] op_sel_hi:[1,0]
	v_pk_mul_f32 v[92:93], v[92:93], v[18:19] op_sel_hi:[1,0]
	v_pk_mul_f32 v[94:95], v[94:95], v[18:19] op_sel_hi:[1,0]
	v_pk_mul_f32 v[96:97], v[96:97], v[18:19] op_sel_hi:[1,0]
	v_pk_mul_f32 v[98:99], v[98:99], v[18:19] op_sel_hi:[1,0]
	v_pk_mul_f32 v[100:101], v[100:101], v[18:19] op_sel_hi:[1,0]
	v_pk_mul_f32 v[102:103], v[102:103], v[18:19] op_sel_hi:[1,0]
	v_pk_mul_f32 v[104:105], v[104:105], v[18:19] op_sel_hi:[1,0]
	v_pk_mul_f32 v[106:107], v[106:107], v[18:19] op_sel_hi:[1,0]
	v_pk_mul_f32 v[108:109], v[108:109], v[18:19] op_sel_hi:[1,0]
	v_pk_mul_f32 v[110:111], v[110:111], v[18:19] op_sel_hi:[1,0]
	v_pk_mul_f32 v[112:113], v[112:113], v[18:19] op_sel_hi:[1,0]
	v_pk_mul_f32 v[114:115], v[114:115], v[18:19] op_sel_hi:[1,0]
	v_pk_mul_f32 v[84:85], v[20:21], v[84:85]
	v_pk_mul_f32 v[86:87], v[22:23], v[86:87]
	v_pk_mul_f32 v[88:89], v[24:25], v[88:89]
	v_pk_mul_f32 v[90:91], v[26:27], v[90:91]
	v_pk_mul_f32 v[92:93], v[28:29], v[92:93]
	v_pk_mul_f32 v[94:95], v[30:31], v[94:95]
	v_pk_mul_f32 v[96:97], v[32:33], v[96:97]
	v_pk_mul_f32 v[98:99], v[34:35], v[98:99]
	v_pk_mul_f32 v[100:101], v[36:37], v[100:101]
	v_pk_mul_f32 v[102:103], v[38:39], v[102:103]
	v_pk_mul_f32 v[104:105], v[40:41], v[104:105]
	v_pk_mul_f32 v[106:107], v[42:43], v[106:107]
	v_pk_mul_f32 v[108:109], v[44:45], v[108:109]
	v_pk_mul_f32 v[110:111], v[46:47], v[110:111]
	v_pk_mul_f32 v[112:113], v[48:49], v[112:113]
	v_pk_mul_f32 v[114:115], v[50:51], v[114:115]
	global_store_dwordx4 v0, v[84:87], s[8:9] offset:-4096
	global_store_dwordx4 v0, v[88:91], s[8:9] offset:-3072
	global_store_dwordx4 v0, v[92:95], s[8:9] offset:-2048
	global_store_dwordx4 v0, v[96:99], s[8:9] offset:-1024
	global_store_dwordx4 v0, v[100:103], s[8:9] offset:0
	global_store_dwordx4 v0, v[104:107], s[8:9] offset:1024
	global_store_dwordx4 v0, v[108:111], s[8:9] offset:2048
	global_store_dwordx4 v0, v[112:115], s[8:9] offset:3072
	s_add_u32 s8, s8, 0x1000000
	s_addc_u32 s9, s9, 0
	s_add_u32 s6, s6, 0x1000000
	s_addc_u32 s7, s7, 0
	global_load_dwordx4 v[84:87], v0, s[6:7] offset:-4096
	global_load_dwordx4 v[88:91], v0, s[6:7] offset:-3072
	global_load_dwordx4 v[92:95], v0, s[6:7] offset:-2048
	global_load_dwordx4 v[96:99], v0, s[6:7] offset:-1024
	global_load_dwordx4 v[100:103], v0, s[6:7] offset:0
	global_load_dwordx4 v[104:107], v0, s[6:7] offset:1024
	global_load_dwordx4 v[108:111], v0, s[6:7] offset:2048
	global_load_dwordx4 v[112:115], v0, s[6:7] offset:3072
	s_waitcnt vmcnt(16)
	v_mul_f32_e32 v10, v52, v52
	v_mul_f32_e32 v11, v53, v53
	v_mul_f32_e32 v12, v54, v54
	v_mul_f32_e32 v13, v55, v55
	v_fmac_f32_e32 v10, v56, v56
	v_fmac_f32_e32 v11, v57, v57
	v_fmac_f32_e32 v12, v58, v58
	v_fmac_f32_e32 v13, v59, v59
	v_fmac_f32_e32 v10, v60, v60
	v_fmac_f32_e32 v11, v61, v61
	v_fmac_f32_e32 v12, v62, v62
	v_fmac_f32_e32 v13, v63, v63
	v_fmac_f32_e32 v10, v64, v64
	v_fmac_f32_e32 v11, v65, v65
	v_fmac_f32_e32 v12, v66, v66
	v_fmac_f32_e32 v13, v67, v67
	v_fmac_f32_e32 v10, v68, v68
	v_fmac_f32_e32 v11, v69, v69
	v_fmac_f32_e32 v12, v70, v70
	v_fmac_f32_e32 v13, v71, v71
	v_fmac_f32_e32 v10, v72, v72
	v_fmac_f32_e32 v11, v73, v73
	v_fmac_f32_e32 v12, v74, v74
	v_fmac_f32_e32 v13, v75, v75
	v_fmac_f32_e32 v10, v76, v76
	v_fmac_f32_e32 v11, v77, v77
	v_fmac_f32_e32 v12, v78, v78
	v_fmac_f32_e32 v13, v79, v79
	v_fmac_f32_e32 v10, v80, v80
	v_fmac_f32_e32 v11, v81, v81
	v_fmac_f32_e32 v12, v82, v82
	v_fmac_f32_e32 v13, v83, v83
	v_add_f32_e32 v10, v10, v11
	v_add_f32_e32 v12, v12, v13
	v_add_f32_e32 v10, v10, v12
	ds_bpermute_b32 v11, v2, v10
	s_waitcnt lgkmcnt(0)
	v_add_f32_e32 v10, v10, v11
	ds_bpermute_b32 v11, v3, v10
	s_waitcnt lgkmcnt(0)
	v_add_f32_e32 v10, v10, v11
	ds_bpermute_b32 v11, v4, v10
	s_waitcnt lgkmcnt(0)
	v_add_f32_e32 v10, v10, v11
	ds_bpermute_b32 v11, v5, v10
	s_waitcnt lgkmcnt(0)
	v_add_f32_e32 v10, v10, v11
	ds_bpermute_b32 v11, v6, v10
	s_waitcnt lgkmcnt(0)
	v_add_f32_e32 v10, v10, v11
	ds_bpermute_b32 v11, v7, v10
	s_waitcnt lgkmcnt(0)
	v_add_f32_e32 v10, v10, v11
	v_fmamk_f32 v10, v10, 0x3a000000, v8
	v_mul_f32_e32 v11, 0x4f800000, v10
	v_cmp_gt_f32_e32 vcc, s0, v10
	s_nop 1
	v_cndmask_b32_e32 v10, v10, v11, vcc
	v_sqrt_f32_e32 v11, v10
	s_nop 0
	v_add_u32_e32 v12, -1, v11
	v_add_u32_e32 v13, 1, v11
	v_fma_f32 v14, -v12, v11, v10
	v_fma_f32 v15, -v13, v11, v10
	v_cmp_ge_f32_e64 s[2:3], 0, v14
	s_nop 1
	v_cndmask_b32_e64 v11, v11, v12, s[2:3]
	v_cmp_lt_f32_e64 s[2:3], 0, v15
	s_nop 1
	v_cndmask_b32_e64 v11, v11, v13, s[2:3]
	v_mul_f32_e32 v12, 0x37800000, v11
	v_cndmask_b32_e32 v11, v11, v12, vcc
	v_cmp_class_f32_e32 vcc, v10, v9
	s_nop 1
	v_cndmask_b32_e32 v10, v11, v10, vcc
	v_div_scale_f32 v11, s[2:3], v10, v10, 1.0
	v_rcp_f32_e32 v12, v11
	v_div_scale_f32 v13, vcc, 1.0, v10, 1.0
	v_fma_f32 v14, -v11, v12, 1.0
	v_fmac_f32_e32 v12, v14, v12
	v_mul_f32_e32 v14, v13, v12
	v_fma_f32 v15, -v11, v14, v13
	v_fmac_f32_e32 v14, v15, v12
	v_fma_f32 v11, -v11, v14, v13
	v_div_fmas_f32 v11, v11, v12, v14
	v_div_fixup_f32 v10, v11, v10, 1.0
	v_mov_b32_e32 v18, v10
	v_pk_mul_f32 v[52:53], v[52:53], v[18:19] op_sel_hi:[1,0]
	v_pk_mul_f32 v[54:55], v[54:55], v[18:19] op_sel_hi:[1,0]
	v_pk_mul_f32 v[56:57], v[56:57], v[18:19] op_sel_hi:[1,0]
	v_pk_mul_f32 v[58:59], v[58:59], v[18:19] op_sel_hi:[1,0]
	v_pk_mul_f32 v[60:61], v[60:61], v[18:19] op_sel_hi:[1,0]
	v_pk_mul_f32 v[62:63], v[62:63], v[18:19] op_sel_hi:[1,0]
	v_pk_mul_f32 v[64:65], v[64:65], v[18:19] op_sel_hi:[1,0]
	v_pk_mul_f32 v[66:67], v[66:67], v[18:19] op_sel_hi:[1,0]
	v_pk_mul_f32 v[68:69], v[68:69], v[18:19] op_sel_hi:[1,0]
	v_pk_mul_f32 v[70:71], v[70:71], v[18:19] op_sel_hi:[1,0]
	v_pk_mul_f32 v[72:73], v[72:73], v[18:19] op_sel_hi:[1,0]
	v_pk_mul_f32 v[74:75], v[74:75], v[18:19] op_sel_hi:[1,0]
	v_pk_mul_f32 v[76:77], v[76:77], v[18:19] op_sel_hi:[1,0]
	v_pk_mul_f32 v[78:79], v[78:79], v[18:19] op_sel_hi:[1,0]
	v_pk_mul_f32 v[80:81], v[80:81], v[18:19] op_sel_hi:[1,0]
	v_pk_mul_f32 v[82:83], v[82:83], v[18:19] op_sel_hi:[1,0]
	v_pk_mul_f32 v[52:53], v[20:21], v[52:53]
	v_pk_mul_f32 v[54:55], v[22:23], v[54:55]
	v_pk_mul_f32 v[56:57], v[24:25], v[56:57]
	v_pk_mul_f32 v[58:59], v[26:27], v[58:59]
	v_pk_mul_f32 v[60:61], v[28:29], v[60:61]
	v_pk_mul_f32 v[62:63], v[30:31], v[62:63]
	v_pk_mul_f32 v[64:65], v[32:33], v[64:65]
	v_pk_mul_f32 v[66:67], v[34:35], v[66:67]
	v_pk_mul_f32 v[68:69], v[36:37], v[68:69]
	v_pk_mul_f32 v[70:71], v[38:39], v[70:71]
	v_pk_mul_f32 v[72:73], v[40:41], v[72:73]
	v_pk_mul_f32 v[74:75], v[42:43], v[74:75]
	v_pk_mul_f32 v[76:77], v[44:45], v[76:77]
	v_pk_mul_f32 v[78:79], v[46:47], v[78:79]
	v_pk_mul_f32 v[80:81], v[48:49], v[80:81]
	v_pk_mul_f32 v[82:83], v[50:51], v[82:83]
	global_store_dwordx4 v0, v[52:55], s[8:9] offset:-4096
	global_store_dwordx4 v0, v[56:59], s[8:9] offset:-3072
	global_store_dwordx4 v0, v[60:63], s[8:9] offset:-2048
	global_store_dwordx4 v0, v[64:67], s[8:9] offset:-1024
	global_store_dwordx4 v0, v[68:71], s[8:9] offset:0
	global_store_dwordx4 v0, v[72:75], s[8:9] offset:1024
	global_store_dwordx4 v0, v[76:79], s[8:9] offset:2048
	global_store_dwordx4 v0, v[80:83], s[8:9] offset:3072
	s_add_u32 s8, s8, 0x1000000
	s_addc_u32 s9, s9, 0
	s_waitcnt vmcnt(8)
	v_mul_f32_e32 v10, v84, v84
	v_mul_f32_e32 v11, v85, v85
	v_mul_f32_e32 v12, v86, v86
	v_mul_f32_e32 v13, v87, v87
	v_fmac_f32_e32 v10, v88, v88
	v_fmac_f32_e32 v11, v89, v89
	v_fmac_f32_e32 v12, v90, v90
	v_fmac_f32_e32 v13, v91, v91
	v_fmac_f32_e32 v10, v92, v92
	v_fmac_f32_e32 v11, v93, v93
	v_fmac_f32_e32 v12, v94, v94
	v_fmac_f32_e32 v13, v95, v95
	v_fmac_f32_e32 v10, v96, v96
	v_fmac_f32_e32 v11, v97, v97
	v_fmac_f32_e32 v12, v98, v98
	v_fmac_f32_e32 v13, v99, v99
	v_fmac_f32_e32 v10, v100, v100
	v_fmac_f32_e32 v11, v101, v101
	v_fmac_f32_e32 v12, v102, v102
	v_fmac_f32_e32 v13, v103, v103
	v_fmac_f32_e32 v10, v104, v104
	v_fmac_f32_e32 v11, v105, v105
	v_fmac_f32_e32 v12, v106, v106
	v_fmac_f32_e32 v13, v107, v107
	v_fmac_f32_e32 v10, v108, v108
	v_fmac_f32_e32 v11, v109, v109
	v_fmac_f32_e32 v12, v110, v110
	v_fmac_f32_e32 v13, v111, v111
	v_fmac_f32_e32 v10, v112, v112
	v_fmac_f32_e32 v11, v113, v113
	v_fmac_f32_e32 v12, v114, v114
	v_fmac_f32_e32 v13, v115, v115
	v_add_f32_e32 v10, v10, v11
	v_add_f32_e32 v12, v12, v13
	v_add_f32_e32 v10, v10, v12
	ds_bpermute_b32 v11, v2, v10
	s_waitcnt lgkmcnt(0)
	v_add_f32_e32 v10, v10, v11
	ds_bpermute_b32 v11, v3, v10
	s_waitcnt lgkmcnt(0)
	v_add_f32_e32 v10, v10, v11
	ds_bpermute_b32 v11, v4, v10
	s_waitcnt lgkmcnt(0)
	v_add_f32_e32 v10, v10, v11
	ds_bpermute_b32 v11, v5, v10
	s_waitcnt lgkmcnt(0)
	v_add_f32_e32 v10, v10, v11
	ds_bpermute_b32 v11, v6, v10
	s_waitcnt lgkmcnt(0)
	v_add_f32_e32 v10, v10, v11
	ds_bpermute_b32 v11, v7, v10
	s_waitcnt lgkmcnt(0)
	v_add_f32_e32 v10, v10, v11
	v_fmamk_f32 v10, v10, 0x3a000000, v8
	v_mul_f32_e32 v11, 0x4f800000, v10
	v_cmp_gt_f32_e32 vcc, s0, v10
	s_nop 1
	v_cndmask_b32_e32 v10, v10, v11, vcc
	v_sqrt_f32_e32 v11, v10
	s_nop 0
	v_add_u32_e32 v12, -1, v11
	v_add_u32_e32 v13, 1, v11
	v_fma_f32 v14, -v12, v11, v10
	v_fma_f32 v15, -v13, v11, v10
	v_cmp_ge_f32_e64 s[2:3], 0, v14
	s_nop 1
	v_cndmask_b32_e64 v11, v11, v12, s[2:3]
	v_cmp_lt_f32_e64 s[2:3], 0, v15
	s_nop 1
	v_cndmask_b32_e64 v11, v11, v13, s[2:3]
	v_mul_f32_e32 v12, 0x37800000, v11
	v_cndmask_b32_e32 v11, v11, v12, vcc
	v_cmp_class_f32_e32 vcc, v10, v9
	s_nop 1
	v_cndmask_b32_e32 v10, v11, v10, vcc
	v_div_scale_f32 v11, s[2:3], v10, v10, 1.0
	v_rcp_f32_e32 v12, v11
	v_div_scale_f32 v13, vcc, 1.0, v10, 1.0
	v_fma_f32 v14, -v11, v12, 1.0
	v_fmac_f32_e32 v12, v14, v12
	v_mul_f32_e32 v14, v13, v12
	v_fma_f32 v15, -v11, v14, v13
	v_fmac_f32_e32 v14, v15, v12
	v_fma_f32 v11, -v11, v14, v13
	v_div_fmas_f32 v11, v11, v12, v14
	v_div_fixup_f32 v10, v11, v10, 1.0
	v_mov_b32_e32 v18, v10
	v_pk_mul_f32 v[84:85], v[84:85], v[18:19] op_sel_hi:[1,0]
	v_pk_mul_f32 v[86:87], v[86:87], v[18:19] op_sel_hi:[1,0]
	v_pk_mul_f32 v[88:89], v[88:89], v[18:19] op_sel_hi:[1,0]
	v_pk_mul_f32 v[90:91], v[90:91], v[18:19] op_sel_hi:[1,0]
	v_pk_mul_f32 v[92:93], v[92:93], v[18:19] op_sel_hi:[1,0]
	v_pk_mul_f32 v[94:95], v[94:95], v[18:19] op_sel_hi:[1,0]
	v_pk_mul_f32 v[96:97], v[96:97], v[18:19] op_sel_hi:[1,0]
	v_pk_mul_f32 v[98:99], v[98:99], v[18:19] op_sel_hi:[1,0]
	v_pk_mul_f32 v[100:101], v[100:101], v[18:19] op_sel_hi:[1,0]
	v_pk_mul_f32 v[102:103], v[102:103], v[18:19] op_sel_hi:[1,0]
	v_pk_mul_f32 v[104:105], v[104:105], v[18:19] op_sel_hi:[1,0]
	v_pk_mul_f32 v[106:107], v[106:107], v[18:19] op_sel_hi:[1,0]
	v_pk_mul_f32 v[108:109], v[108:109], v[18:19] op_sel_hi:[1,0]
	v_pk_mul_f32 v[110:111], v[110:111], v[18:19] op_sel_hi:[1,0]
	v_pk_mul_f32 v[112:113], v[112:113], v[18:19] op_sel_hi:[1,0]
	v_pk_mul_f32 v[114:115], v[114:115], v[18:19] op_sel_hi:[1,0]
	v_pk_mul_f32 v[84:85], v[20:21], v[84:85]
	v_pk_mul_f32 v[86:87], v[22:23], v[86:87]
	v_pk_mul_f32 v[88:89], v[24:25], v[88:89]
	v_pk_mul_f32 v[90:91], v[26:27], v[90:91]
	v_pk_mul_f32 v[92:93], v[28:29], v[92:93]
	v_pk_mul_f32 v[94:95], v[30:31], v[94:95]
	v_pk_mul_f32 v[96:97], v[32:33], v[96:97]
	v_pk_mul_f32 v[98:99], v[34:35], v[98:99]
	v_pk_mul_f32 v[100:101], v[36:37], v[100:101]
	v_pk_mul_f32 v[102:103], v[38:39], v[102:103]
	v_pk_mul_f32 v[104:105], v[40:41], v[104:105]
	v_pk_mul_f32 v[106:107], v[42:43], v[106:107]
	v_pk_mul_f32 v[108:109], v[44:45], v[108:109]
	v_pk_mul_f32 v[110:111], v[46:47], v[110:111]
	v_pk_mul_f32 v[112:113], v[48:49], v[112:113]
	v_pk_mul_f32 v[114:115], v[50:51], v[114:115]
	global_store_dwordx4 v0, v[84:87], s[8:9] offset:-4096
	global_store_dwordx4 v0, v[88:91], s[8:9] offset:-3072
	global_store_dwordx4 v0, v[92:95], s[8:9] offset:-2048
	global_store_dwordx4 v0, v[96:99], s[8:9] offset:-1024
	global_store_dwordx4 v0, v[100:103], s[8:9] offset:0
	global_store_dwordx4 v0, v[104:107], s[8:9] offset:1024
	global_store_dwordx4 v0, v[108:111], s[8:9] offset:2048
	global_store_dwordx4 v0, v[112:115], s[8:9] offset:3072

	.amdhsa_kernel _Z6mk_fwd4Args
		.amdhsa_group_segment_fixed_size 0
		.amdhsa_private_segment_fixed_size 0
		.amdhsa_kernarg_size 456
		.amdhsa_user_sgpr_count 2
		.amdhsa_user_sgpr_dispatch_ptr 0
		.amdhsa_user_sgpr_queue_ptr 0
		.amdhsa_user_sgpr_kernarg_segment_ptr 1
		.amdhsa_user_sgpr_dispatch_id 0
		.amdhsa_user_sgpr_kernarg_preload_length 0
		.amdhsa_user_sgpr_kernarg_preload_offset 0
		.amdhsa_user_sgpr_private_segment_size 0
		.amdhsa_uses_dynamic_stack 0
		.amdhsa_enable_private_segment 0
		.amdhsa_system_sgpr_workgroup_id_x 1
		.amdhsa_system_sgpr_workgroup_id_y 0
		.amdhsa_system_sgpr_workgroup_id_z 0
		.amdhsa_system_sgpr_workgroup_info 0
		.amdhsa_system_vgpr_workitem_id 2
		.amdhsa_next_free_vgpr 254
		.amdhsa_next_free_sgpr 102
		.amdhsa_accum_offset 256
		.amdhsa_reserve_vcc 1
		.amdhsa_float_round_mode_32 0
		.amdhsa_float_round_mode_16_64 0
		.amdhsa_float_denorm_mode_32 3
		.amdhsa_float_denorm_mode_16_64 3
		.amdhsa_dx10_clamp 1
		.amdhsa_ieee_mode 1
		.amdhsa_fp16_overflow 0
		.amdhsa_tg_split 0
		.amdhsa_exception_fp_ieee_invalid_op 0
		.amdhsa_exception_fp_denorm_src 0
		.amdhsa_exception_fp_ieee_div_zero 0
		.amdhsa_exception_fp_ieee_overflow 0
		.amdhsa_exception_fp_ieee_underflow 0
		.amdhsa_exception_fp_ieee_inexact 0
		.amdhsa_exception_int_div_zero 0
	.end_amdhsa_kernel

amdhsa.kernels:
  - .agpr_count:     0
    .args:
      - .offset:         0
        .size:           200
        .value_kind:     by_value
      - .offset:         200
        .size:           4
        .value_kind:     hidden_block_count_x
      - .offset:         204
        .size:           4
        .value_kind:     hidden_block_count_y
      - .offset:         208
        .size:           4
        .value_kind:     hidden_block_count_z
      - .offset:         212
        .size:           2
        .value_kind:     hidden_group_size_x
      - .offset:         214
        .size:           2
        .value_kind:     hidden_group_size_y
      - .offset:         216
        .size:           2
        .value_kind:     hidden_group_size_z
      - .offset:         218
        .size:           2
        .value_kind:     hidden_remainder_x
      - .offset:         220
        .size:           2
        .value_kind:     hidden_remainder_y
      - .offset:         222
        .size:           2
        .value_kind:     hidden_remainder_z
      - .offset:         240
        .size:           8
        .value_kind:     hidden_global_offset_x
      - .offset:         248
        .size:           8
        .value_kind:     hidden_global_offset_y
      - .offset:         256
        .size:           8
        .value_kind:     hidden_global_offset_z
      - .offset:         264
        .size:           2
        .value_kind:     hidden_grid_dims
      - .offset:         288
        .size:           8
        .value_kind:     hidden_multigrid_sync_arg
      - .offset:         320
        .size:           4
        .value_kind:     hidden_dynamic_lds_size
    .group_segment_fixed_size: 0
    .kernarg_segment_align: 8
    .kernarg_segment_size: 456
    .language:       OpenCL C
    .language_version:
      - 2
      - 0
    .max_flat_workgroup_size: 512
    .name:           _Z6mk_fwd4Args
    .private_segment_fixed_size: 0
    .sgpr_count:     108
    .sgpr_spill_count: 20
    .symbol:         _Z6mk_fwd4Args.kd
    .uniform_work_group_size: 1
    .uses_dynamic_stack: false
    .vgpr_count:     254
    .vgpr_spill_count: 0
    .wavefront_size: 64
